# fused-RMSNorm GEMM epilogues: 1/sqrt(mean+eps) by v_rsq_f32 (f32, as the reference's rsqrt) instead of the 33-instruction precise sqrt+divide expansion, 8 per tile; on top of the norm-phase loop rewri
# baseline (speedup 1.0000x reference)
;     __device__ __forceinline__ void operator()(const f32x4 (&acc)[2][2][4][2], const Unit& u, int wr, int wc, int fr, int fq) const {
;     ...
;         if (ss) { const float* swp = sw + (size_t)((u.pm * BM) / rows_per_batch) * sw_stride + u.pn * BM + wc * 32 + 8 * fq;
; #pragma unroll
;             for (int bj = 0; bj < 2; ++bj)
; #pragma unroll
;                 for (int n = 0; n < 2; ++n) swv[bj][n] = *(const f32x4*)(swp + bj * HALF + 4 * n); }
; #pragma unroll
;         for (int ai = 0; ai < 2; ++ai)
; #pragma unroll
;             for (int m = 0; m < 4; ++m) { const int row = row0 + ai * HALF + m * 16; bf16_t* rowp = base + (size_t)row * ldc + col0;
;                 float inv = 1.f;
;                 if (ss) { const f32x4* sp = (const f32x4*)(ss + (size_t)row * 32 + fq * 8); const f32x4 p0 = sp[0], p1 = sp[1];
;                     float s = ((p0[0] + p0[1]) + (p0[2] + p0[3])) + ((p1[0] + p1[1]) + (p1[2] + p1[3]));
;                     s += __shfl_xor(s, 16); s += __shfl_xor(s, 32); inv = 1.0f / sqrtf(s * (1.f / 2048.f) + 1e-6f); }
;                 f32x4 va[2][2];
; #pragma unroll
;                 for (int bj = 0; bj < 2; ++bj) { f32x4 v0 = acc[ai][bj][m][0], v1 = acc[ai][bj][m][1];
;                     if (ss) { v0 = v0 * inv + swv[bj][0]; v1 = v1 * inv + swv[bj][1]; }
;                     if (ACT == 2) { v0 = __builtin_elementwise_max(v0, (f32x4){0.f, 0.f, 0.f, 0.f}); v1 = __builtin_elementwise_max(v1, (f32x4){0.f, 0.f, 0.f, 0.f}); v0 = v0 * v0; v1 = v1 * v1; }
;                     v0 = v0 * sc; v1 = v1 * sc;
;                     if (do_nrm) { float s2 = ((v0[0] * v0[0] + v0[1] * v0[1]) + (v0[2] * v0[2] + v0[3] * v0[3])) + ((v1[0] * v1[0] + v1[1] * v1[1]) + (v1[2] * v1[2] + v1[3] * v1[3]));
;                         s2 += __shfl_xor(s2, 16); s2 += __shfl_xor(s2, 32);
;                         if (fq == 0) nrm[((size_t)(((u.pn >> 3) * 4 + (row >> 12)) * 16 + (u.pn & 7) * 2 + bj) * 4096 + (row & 4095)) * 4 + wc] = s2; }
;                     va[bj][0] = v0; va[bj][1] = v1; }
;                 if (cu_out != nullptr && u.pn >= cu_from) {
;                     const f32x4 p0 = va[0][0] * va[1][0], p1 = va[0][1] * va[1][1];
;                     u32x4 w; w.x = cvt_pk_bf16(p0[0], p0[1]); w.y = cvt_pk_bf16(p0[2], p0[3]); w.z = cvt_pk_bf16(p1[0], p1[1]); w.w = cvt_pk_bf16(p1[2], p1[3]);
.LBB0_58:
	v_lshl_add_u32 v158, s63, 8, v162
	v_ashrrev_i32_e32 v159, 31, v158
	v_lshlrev_b64 v[64:65], 7, v[158:159]
	v_lshl_add_u64 v[64:65], v[150:151], 0, v[64:65]
	global_load_dwordx4 v[168:171], v[64:65], off
	global_load_dwordx4 v[172:175], v[64:65], off offset:16
	s_ashr_i32 s25, s63, 31
	s_lshr_b32 s25, s25, 28
	s_add_i32 s25, s63, s25
	s_ashr_i32 s42, s25, 4
	s_ashr_i32 s43, s42, 31
	s_lshl_b32 s28, s64, 8
	s_lshl_b64 s[42:43], s[42:43], 15
	s_add_u32 s25, s49, s42
	s_addc_u32 s27, s54, s43
	s_ashr_i32 s29, s28, 31
	s_lshl_b64 s[42:43], s[28:29], 2
	s_add_u32 s25, s25, s42
	s_addc_u32 s27, s27, s43
	s_add_u32 s42, s25, s62
	s_addc_u32 s43, s27, 0
	global_load_dwordx4 v[76:79], v166, s[42:43]
	global_load_dwordx4 v[72:75], v166, s[42:43] offset:16
	global_load_dwordx4 v[68:71], v166, s[42:43] offset:512
	global_load_dwordx4 v[64:67], v166, s[42:43] offset:528
	v_cmp_lt_i32_e32 vcc, v232, v220
	v_readlane_b32 s72, v255, 9
	v_readlane_b32 s73, v255, 10
	v_cndmask_b32_e32 v156, v217, v232, vcc
	v_lshlrev_b32_e32 v167, 2, v156
	v_cmp_lt_i32_e32 vcc, v226, v220
	s_waitcnt vmcnt(0)
	v_mov_b32_e32 v156, v168
	v_mov_b32_e32 v157, v172
	v_mov_b32_e32 v172, v169
	v_mov_b32_e32 v160, v170
	v_mov_b32_e32 v161, v174
	v_mov_b32_e32 v174, v171
	v_pk_add_f32 v[156:157], v[156:157], v[172:173]
	v_pk_add_f32 v[160:161], v[160:161], v[174:175]
	v_lshlrev_b64 v[170:171], 14, v[158:159]
	v_pk_add_f32 v[156:157], v[156:157], v[160:161]
	v_cndmask_b32_e32 v161, v217, v226, vcc
	v_add_f32_e32 v157, v156, v157
	ds_bpermute_b32 v160, v167, v157
	v_lshlrev_b32_e32 v168, 2, v161
	v_or_b32_e32 v156, s28, v164
	s_waitcnt lgkmcnt(0)
	v_add_f32_e32 v169, v157, v160
	ds_bpermute_b32 v172, v168, v169
	v_or_b32_e32 v160, 16, v158
	v_ashrrev_i32_e32 v157, 31, v156
	v_ashrrev_i32_e32 v161, 31, v160
	v_lshl_add_u64 v[156:157], v[156:157], 1, s[16:17]
	s_waitcnt lgkmcnt(0)
	v_add_f32_e32 v159, v169, v172
	v_fmamk_f32 v159, v159, 0x3a000000, v215
	v_rsq_f32_e32 v174, v159
	s_nop 0
	v_lshlrev_b64 v[172:173], 7, v[160:161]
	v_lshl_add_u64 v[170:171], v[156:157], 0, v[170:171]
	v_lshl_add_u64 v[172:173], v[150:151], 0, v[172:173]
	v_pk_fma_f32 v[142:143], v[142:143], v[174:175], v[78:79] op_sel_hi:[1,0,1]
	v_pk_fma_f32 v[140:141], v[140:141], v[174:175], v[76:77] op_sel_hi:[1,0,1]
	v_pk_fma_f32 v[138:139], v[138:139], v[174:175], v[74:75] op_sel_hi:[1,0,1]
	v_pk_fma_f32 v[136:137], v[136:137], v[174:175], v[72:73] op_sel_hi:[1,0,1]
	v_pk_fma_f32 v[130:131], v[130:131], v[174:175], v[66:67] op_sel_hi:[1,0,1]
	v_pk_fma_f32 v[128:129], v[128:129], v[174:175], v[64:65] op_sel_hi:[1,0,1]
	v_pk_fma_f32 v[134:135], v[134:135], v[174:175], v[70:71] op_sel_hi:[1,0,1]
	v_pk_fma_f32 v[132:133], v[132:133], v[174:175], v[68:69] op_sel_hi:[1,0,1]
	v_max_f32_e32 v141, 0, v141
	v_max_f32_e32 v140, 0, v140
	v_max_f32_e32 v143, 0, v143
	v_max_f32_e32 v142, 0, v142
	v_max_f32_e32 v137, 0, v137
	v_max_f32_e32 v136, 0, v136
	v_max_f32_e32 v139, 0, v139
	v_max_f32_e32 v138, 0, v138
	v_max_f32_e32 v129, 0, v129
	v_max_f32_e32 v128, 0, v128
	v_max_f32_e32 v131, 0, v131
	v_max_f32_e32 v130, 0, v130
	v_max_f32_e32 v133, 0, v133
	v_max_f32_e32 v132, 0, v132
	v_max_f32_e32 v135, 0, v135
	v_max_f32_e32 v134, 0, v134
	v_pk_mul_f32 v[142:143], v[142:143], v[142:143]
	v_pk_mul_f32 v[140:141], v[140:141], v[140:141]
	v_pk_mul_f32 v[138:139], v[138:139], v[138:139]
	v_pk_mul_f32 v[136:137], v[136:137], v[136:137]
	v_pk_mul_f32 v[174:175], v[130:131], v[130:131]
	v_pk_mul_f32 v[176:177], v[128:129], v[128:129]
	v_cvt_pk_bf16_f32 v128, v140, v141
	v_cvt_pk_bf16_f32 v129, v142, v143
	v_cvt_pk_bf16_f32 v130, v136, v137
	v_cvt_pk_bf16_f32 v131, v138, v139
	v_pk_mul_f32 v[134:135], v[134:135], v[134:135]
	v_pk_mul_f32 v[132:133], v[132:133], v[132:133]
	global_store_dwordx4 v[170:171], v[128:131], off
	s_nop 1
	v_cvt_pk_bf16_f32 v128, v132, v133
	v_cvt_pk_bf16_f32 v129, v134, v135
	v_cvt_pk_bf16_f32 v130, v176, v177
	v_cvt_pk_bf16_f32 v131, v174, v175
	global_store_dwordx4 v[170:171], v[128:131], off offset:256
	global_load_dwordx4 v[128:131], v[172:173], off
	s_nop 0
	global_load_dwordx4 v[132:135], v[172:173], off offset:16
	s_waitcnt vmcnt(1)
	v_mov_b32_e32 v136, v128
	s_waitcnt vmcnt(0)
	v_mov_b32_e32 v137, v132
	v_mov_b32_e32 v132, v129
	v_mov_b32_e32 v128, v130
	v_mov_b32_e32 v129, v134
	v_mov_b32_e32 v134, v131
	v_pk_add_f32 v[130:131], v[136:137], v[132:133]
	v_pk_add_f32 v[128:129], v[128:129], v[134:135]
	s_nop 0
	v_pk_add_f32 v[128:129], v[130:131], v[128:129]
	s_nop 0
	v_add_f32_e32 v128, v128, v129
	ds_bpermute_b32 v129, v167, v128
	s_waitcnt lgkmcnt(0)
	v_add_f32_e32 v130, v128, v129
	ds_bpermute_b32 v131, v168, v130
	v_or_b32_e32 v128, 32, v158
	v_ashrrev_i32_e32 v129, 31, v128
	v_lshlrev_b64 v[132:133], 7, v[128:129]
	v_lshl_add_u64 v[132:133], v[150:151], 0, v[132:133]
	s_waitcnt lgkmcnt(0)
;     __device__ __forceinline__ void operator()(const f32x4 (&acc)[2][2][4][2], const Unit& u, int wr, int wc, int fr, int fq) const {
;     ...
;             for (int m = 0; m < 4; ++m) { const int row = row0 + ai * HALF + m * 16; bf16_t* rowp = base + (size_t)row * ldc + col0;
;                 float inv = 1.f;
;                 if (ss) { const f32x4* sp = (const f32x4*)(ss + (size_t)row * 32 + fq * 8); const f32x4 p0 = sp[0], p1 = sp[1];
;                     float s = ((p0[0] + p0[1]) + (p0[2] + p0[3])) + ((p1[0] + p1[1]) + (p1[2] + p1[3]));
;                     s += __shfl_xor(s, 16); s += __shfl_xor(s, 32); inv = 1.0f / sqrtf(s * (1.f / 2048.f) + 1e-6f); }
;                 f32x4 va[2][2];
; #pragma unroll
;                 for (int bj = 0; bj < 2; ++bj) { f32x4 v0 = acc[ai][bj][m][0], v1 = acc[ai][bj][m][1];
;                     if (ss) { v0 = v0 * inv + swv[bj][0]; v1 = v1 * inv + swv[bj][1]; }
;                     if (ACT == 2) { v0 = __builtin_elementwise_max(v0, (f32x4){0.f, 0.f, 0.f, 0.f}); v1 = __builtin_elementwise_max(v1, (f32x4){0.f, 0.f, 0.f, 0.f}); v0 = v0 * v0; v1 = v1 * v1; }
;                     v0 = v0 * sc; v1 = v1 * sc;
;                     if (do_nrm) { float s2 = ((v0[0] * v0[0] + v0[1] * v0[1]) + (v0[2] * v0[2] + v0[3] * v0[3])) + ((v1[0] * v1[0] + v1[1] * v1[1]) + (v1[2] * v1[2] + v1[3] * v1[3]));
;                         s2 += __shfl_xor(s2, 16); s2 += __shfl_xor(s2, 32);
;                         if (fq == 0) nrm[((size_t)(((u.pn >> 3) * 4 + (row >> 12)) * 16 + (u.pn & 7) * 2 + bj) * 4096 + (row & 4095)) * 4 + wc] = s2; }
;                     va[bj][0] = v0; va[bj][1] = v1; }
;                 if (cu_out != nullptr && u.pn >= cu_from) {
;                     const f32x4 p0 = va[0][0] * va[1][0], p1 = va[0][1] * va[1][1];
;                     u32x4 w; w.x = cvt_pk_bf16(p0[0], p0[1]); w.y = cvt_pk_bf16(p0[2], p0[3]); w.z = cvt_pk_bf16(p1[0], p1[1]); w.w = cvt_pk_bf16(p1[2], p1[3]);
;                     *(u32x4*)(cu_out + (size_t)row * ldc + (u.pn - cu_from) * HALF + wc * 32 + 8 * fq) = w;
;                 } else {
; #pragma unroll
;                     for (int bj = 0; bj < 2; ++bj) { const f32x4 v0 = va[bj][0], v1 = va[bj][1];
;                         u32x4 w; w.x = cvt_pk_bf16(v0[0], v0[1]); w.y = cvt_pk_bf16(v0[2], v0[3]); w.z = cvt_pk_bf16(v1[0], v1[1]); w.w = cvt_pk_bf16(v1[2], v1[3]);
	v_add_f32_e32 v130, v130, v131
	v_fmamk_f32 v130, v130, 0x3a000000, v215
	v_rsq_f32_e32 v134, v130
	s_nop 0
	v_lshlrev_b64 v[130:131], 14, v[160:161]
	v_lshl_add_u64 v[130:131], v[156:157], 0, v[130:131]
	v_pk_fma_f32 v[126:127], v[126:127], v[134:135], v[78:79] op_sel_hi:[1,0,1]
	v_pk_fma_f32 v[124:125], v[124:125], v[134:135], v[76:77] op_sel_hi:[1,0,1]
	v_pk_fma_f32 v[122:123], v[122:123], v[134:135], v[74:75] op_sel_hi:[1,0,1]
	v_pk_fma_f32 v[120:121], v[120:121], v[134:135], v[72:73] op_sel_hi:[1,0,1]
	v_pk_fma_f32 v[114:115], v[114:115], v[134:135], v[66:67] op_sel_hi:[1,0,1]
	v_pk_fma_f32 v[112:113], v[112:113], v[134:135], v[64:65] op_sel_hi:[1,0,1]
	v_pk_fma_f32 v[118:119], v[118:119], v[134:135], v[70:71] op_sel_hi:[1,0,1]
	v_pk_fma_f32 v[116:117], v[116:117], v[134:135], v[68:69] op_sel_hi:[1,0,1]
	v_max_f32_e32 v125, 0, v125
	v_max_f32_e32 v124, 0, v124
	v_max_f32_e32 v127, 0, v127
	v_max_f32_e32 v126, 0, v126
	v_max_f32_e32 v121, 0, v121
	v_max_f32_e32 v120, 0, v120
	v_max_f32_e32 v123, 0, v123
	v_max_f32_e32 v122, 0, v122
	v_max_f32_e32 v113, 0, v113
	v_max_f32_e32 v112, 0, v112
	v_max_f32_e32 v115, 0, v115
	v_max_f32_e32 v114, 0, v114
	v_max_f32_e32 v117, 0, v117
	v_max_f32_e32 v116, 0, v116
	v_max_f32_e32 v119, 0, v119
	v_max_f32_e32 v118, 0, v118
	v_pk_mul_f32 v[126:127], v[126:127], v[126:127]
	v_pk_mul_f32 v[124:125], v[124:125], v[124:125]
	v_pk_mul_f32 v[122:123], v[122:123], v[122:123]
	v_pk_mul_f32 v[120:121], v[120:121], v[120:121]
	v_pk_mul_f32 v[134:135], v[114:115], v[114:115]
	v_pk_mul_f32 v[136:137], v[112:113], v[112:113]
	v_cvt_pk_bf16_f32 v112, v124, v125
	v_cvt_pk_bf16_f32 v113, v126, v127
	v_cvt_pk_bf16_f32 v114, v120, v121
	v_cvt_pk_bf16_f32 v115, v122, v123
	v_pk_mul_f32 v[118:119], v[118:119], v[118:119]
	v_pk_mul_f32 v[116:117], v[116:117], v[116:117]
	global_store_dwordx4 v[130:131], v[112:115], off
	s_nop 1
	v_cvt_pk_bf16_f32 v112, v116, v117
	v_cvt_pk_bf16_f32 v113, v118, v119
	v_cvt_pk_bf16_f32 v114, v136, v137
	v_cvt_pk_bf16_f32 v115, v134, v135
	global_store_dwordx4 v[130:131], v[112:115], off offset:256
	global_load_dwordx4 v[112:115], v[132:133], off
	s_nop 0
	global_load_dwordx4 v[116:119], v[132:133], off offset:16
	s_waitcnt vmcnt(1)
	v_mov_b32_e32 v120, v112
	s_waitcnt vmcnt(0)
	v_mov_b32_e32 v121, v116
	v_mov_b32_e32 v116, v113
	v_mov_b32_e32 v112, v114
	v_mov_b32_e32 v113, v118
	v_mov_b32_e32 v118, v115
	v_pk_add_f32 v[114:115], v[120:121], v[116:117]
	v_pk_add_f32 v[112:113], v[112:113], v[118:119]
	s_nop 0
	v_pk_add_f32 v[112:113], v[114:115], v[112:113]
	s_nop 0
	v_add_f32_e32 v112, v112, v113
	ds_bpermute_b32 v113, v167, v112
	s_waitcnt lgkmcnt(0)
	v_add_f32_e32 v114, v112, v113
	ds_bpermute_b32 v115, v168, v114
	v_or_b32_e32 v112, 48, v158
	v_ashrrev_i32_e32 v113, 31, v112
	v_lshlrev_b64 v[116:117], 7, v[112:113]
	v_lshl_add_u64 v[116:117], v[150:151], 0, v[116:117]
	s_waitcnt lgkmcnt(0)
	v_add_f32_e32 v114, v114, v115
	v_fmamk_f32 v114, v114, 0x3a000000, v215
	v_rsq_f32_e32 v118, v114
	s_nop 0
	v_lshlrev_b64 v[114:115], 14, v[128:129]
	v_lshl_add_u64 v[114:115], v[156:157], 0, v[114:115]
	v_pk_fma_f32 v[110:111], v[110:111], v[118:119], v[78:79] op_sel_hi:[1,0,1]
	v_pk_fma_f32 v[108:109], v[108:109], v[118:119], v[76:77] op_sel_hi:[1,0,1]
	v_pk_fma_f32 v[106:107], v[106:107], v[118:119], v[74:75] op_sel_hi:[1,0,1]
	v_pk_fma_f32 v[104:105], v[104:105], v[118:119], v[72:73] op_sel_hi:[1,0,1]
	v_pk_fma_f32 v[98:99], v[98:99], v[118:119], v[66:67] op_sel_hi:[1,0,1]
	v_pk_fma_f32 v[96:97], v[96:97], v[118:119], v[64:65] op_sel_hi:[1,0,1]
	v_pk_fma_f32 v[102:103], v[102:103], v[118:119], v[70:71] op_sel_hi:[1,0,1]
	v_pk_fma_f32 v[100:101], v[100:101], v[118:119], v[68:69] op_sel_hi:[1,0,1]
	v_max_f32_e32 v109, 0, v109
	v_max_f32_e32 v108, 0, v108
	v_max_f32_e32 v111, 0, v111
	v_max_f32_e32 v110, 0, v110
	v_max_f32_e32 v105, 0, v105
	v_max_f32_e32 v104, 0, v104
	v_max_f32_e32 v107, 0, v107
	v_max_f32_e32 v106, 0, v106
	v_max_f32_e32 v97, 0, v97
	v_max_f32_e32 v96, 0, v96
	v_max_f32_e32 v99, 0, v99
	v_max_f32_e32 v98, 0, v98
	v_max_f32_e32 v101, 0, v101
	v_max_f32_e32 v100, 0, v100
	v_max_f32_e32 v103, 0, v103
	v_max_f32_e32 v102, 0, v102
	v_pk_mul_f32 v[110:111], v[110:111], v[110:111]
	v_pk_mul_f32 v[108:109], v[108:109], v[108:109]
	v_pk_mul_f32 v[106:107], v[106:107], v[106:107]
	v_pk_mul_f32 v[104:105], v[104:105], v[104:105]
	v_pk_mul_f32 v[118:119], v[98:99], v[98:99]
	v_pk_mul_f32 v[120:121], v[96:97], v[96:97]
	v_cvt_pk_bf16_f32 v96, v108, v109
	v_cvt_pk_bf16_f32 v97, v110, v111
	v_cvt_pk_bf16_f32 v98, v104, v105
	v_cvt_pk_bf16_f32 v99, v106, v107
	v_pk_mul_f32 v[102:103], v[102:103], v[102:103]
	v_pk_mul_f32 v[100:101], v[100:101], v[100:101]
	global_store_dwordx4 v[114:115], v[96:99], off
	s_nop 1
	v_cvt_pk_bf16_f32 v96, v100, v101
	v_cvt_pk_bf16_f32 v97, v102, v103
	v_cvt_pk_bf16_f32 v98, v120, v121
	v_cvt_pk_bf16_f32 v99, v118, v119
	global_store_dwordx4 v[114:115], v[96:99], off offset:256
	global_load_dwordx4 v[96:99], v[116:117], off
	s_nop 0
	global_load_dwordx4 v[100:103], v[116:117], off offset:16
	s_waitcnt vmcnt(1)
	v_mov_b32_e32 v104, v96
	s_waitcnt vmcnt(0)
	v_mov_b32_e32 v105, v100
	v_mov_b32_e32 v100, v97
	v_mov_b32_e32 v96, v98
	v_mov_b32_e32 v97, v102
	v_mov_b32_e32 v102, v99
	v_pk_add_f32 v[98:99], v[104:105], v[100:101]
	v_pk_add_f32 v[96:97], v[96:97], v[102:103]
	s_nop 0
	v_pk_add_f32 v[96:97], v[98:99], v[96:97]
	s_nop 0
	v_add_f32_e32 v96, v96, v97
	ds_bpermute_b32 v97, v167, v96
	s_waitcnt lgkmcnt(0)
	v_add_f32_e32 v98, v96, v97
	ds_bpermute_b32 v99, v168, v98
	v_add_u32_e32 v96, 0x80, v158
	v_ashrrev_i32_e32 v97, 31, v96
	v_lshlrev_b64 v[100:101], 7, v[96:97]
	v_lshl_add_u64 v[100:101], v[150:151], 0, v[100:101]
	s_waitcnt lgkmcnt(0)
;     __device__ __forceinline__ void operator()(const f32x4 (&acc)[2][2][4][2], const Unit& u, int wr, int wc, int fr, int fq) const {
;     ...
;             for (int m = 0; m < 4; ++m) { const int row = row0 + ai * HALF + m * 16; bf16_t* rowp = base + (size_t)row * ldc + col0;
;                 float inv = 1.f;
;                 if (ss) { const f32x4* sp = (const f32x4*)(ss + (size_t)row * 32 + fq * 8); const f32x4 p0 = sp[0], p1 = sp[1];
;                     float s = ((p0[0] + p0[1]) + (p0[2] + p0[3])) + ((p1[0] + p1[1]) + (p1[2] + p1[3]));
;                     s += __shfl_xor(s, 16); s += __shfl_xor(s, 32); inv = 1.0f / sqrtf(s * (1.f / 2048.f) + 1e-6f); }
;                 f32x4 va[2][2];
; #pragma unroll
;                 for (int bj = 0; bj < 2; ++bj) { f32x4 v0 = acc[ai][bj][m][0], v1 = acc[ai][bj][m][1];
;                     if (ss) { v0 = v0 * inv + swv[bj][0]; v1 = v1 * inv + swv[bj][1]; }
;                     if (ACT == 2) { v0 = __builtin_elementwise_max(v0, (f32x4){0.f, 0.f, 0.f, 0.f}); v1 = __builtin_elementwise_max(v1, (f32x4){0.f, 0.f, 0.f, 0.f}); v0 = v0 * v0; v1 = v1 * v1; }
;                     v0 = v0 * sc; v1 = v1 * sc;
;                     if (do_nrm) { float s2 = ((v0[0] * v0[0] + v0[1] * v0[1]) + (v0[2] * v0[2] + v0[3] * v0[3])) + ((v1[0] * v1[0] + v1[1] * v1[1]) + (v1[2] * v1[2] + v1[3] * v1[3]));
;                         s2 += __shfl_xor(s2, 16); s2 += __shfl_xor(s2, 32);
;                         if (fq == 0) nrm[((size_t)(((u.pn >> 3) * 4 + (row >> 12)) * 16 + (u.pn & 7) * 2 + bj) * 4096 + (row & 4095)) * 4 + wc] = s2; }
;                     va[bj][0] = v0; va[bj][1] = v1; }
;                 if (cu_out != nullptr && u.pn >= cu_from) {
;                     const f32x4 p0 = va[0][0] * va[1][0], p1 = va[0][1] * va[1][1];
;                     u32x4 w; w.x = cvt_pk_bf16(p0[0], p0[1]); w.y = cvt_pk_bf16(p0[2], p0[3]); w.z = cvt_pk_bf16(p1[0], p1[1]); w.w = cvt_pk_bf16(p1[2], p1[3]);
;                     *(u32x4*)(cu_out + (size_t)row * ldc + (u.pn - cu_from) * HALF + wc * 32 + 8 * fq) = w;
;                 } else {
; #pragma unroll
;                     for (int bj = 0; bj < 2; ++bj) { const f32x4 v0 = va[bj][0], v1 = va[bj][1];
;                         u32x4 w; w.x = cvt_pk_bf16(v0[0], v0[1]); w.y = cvt_pk_bf16(v0[2], v0[3]); w.z = cvt_pk_bf16(v1[0], v1[1]); w.w = cvt_pk_bf16(v1[2], v1[3]);
	v_add_f32_e32 v98, v98, v99
	v_fmamk_f32 v98, v98, 0x3a000000, v215
	v_rsq_f32_e32 v102, v98
	s_nop 0
	v_lshlrev_b64 v[98:99], 14, v[112:113]
	v_lshl_add_u64 v[98:99], v[156:157], 0, v[98:99]
	v_pk_fma_f32 v[94:95], v[94:95], v[102:103], v[78:79] op_sel_hi:[1,0,1]
	v_pk_fma_f32 v[92:93], v[92:93], v[102:103], v[76:77] op_sel_hi:[1,0,1]
	v_pk_fma_f32 v[90:91], v[90:91], v[102:103], v[74:75] op_sel_hi:[1,0,1]
	v_pk_fma_f32 v[88:89], v[88:89], v[102:103], v[72:73] op_sel_hi:[1,0,1]
	v_pk_fma_f32 v[82:83], v[82:83], v[102:103], v[66:67] op_sel_hi:[1,0,1]
	v_pk_fma_f32 v[80:81], v[80:81], v[102:103], v[64:65] op_sel_hi:[1,0,1]
	v_pk_fma_f32 v[86:87], v[86:87], v[102:103], v[70:71] op_sel_hi:[1,0,1]
	v_pk_fma_f32 v[84:85], v[84:85], v[102:103], v[68:69] op_sel_hi:[1,0,1]
	v_max_f32_e32 v93, 0, v93
	v_max_f32_e32 v92, 0, v92
	v_max_f32_e32 v95, 0, v95
	v_max_f32_e32 v94, 0, v94
	v_max_f32_e32 v89, 0, v89
	v_max_f32_e32 v88, 0, v88
	v_max_f32_e32 v91, 0, v91
	v_max_f32_e32 v90, 0, v90
	v_max_f32_e32 v81, 0, v81
	v_max_f32_e32 v80, 0, v80
	v_max_f32_e32 v83, 0, v83
	v_max_f32_e32 v82, 0, v82
	v_max_f32_e32 v85, 0, v85
	v_max_f32_e32 v84, 0, v84
	v_max_f32_e32 v87, 0, v87
	v_max_f32_e32 v86, 0, v86
	v_pk_mul_f32 v[94:95], v[94:95], v[94:95]
	v_pk_mul_f32 v[92:93], v[92:93], v[92:93]
	v_pk_mul_f32 v[90:91], v[90:91], v[90:91]
	v_pk_mul_f32 v[88:89], v[88:89], v[88:89]
	v_pk_mul_f32 v[102:103], v[82:83], v[82:83]
	v_pk_mul_f32 v[104:105], v[80:81], v[80:81]
	v_cvt_pk_bf16_f32 v80, v92, v93
	v_cvt_pk_bf16_f32 v81, v94, v95
	v_cvt_pk_bf16_f32 v82, v88, v89
	v_cvt_pk_bf16_f32 v83, v90, v91
	v_pk_mul_f32 v[86:87], v[86:87], v[86:87]
	v_pk_mul_f32 v[84:85], v[84:85], v[84:85]
	global_store_dwordx4 v[98:99], v[80:83], off
	s_nop 1
	v_cvt_pk_bf16_f32 v80, v84, v85
	v_cvt_pk_bf16_f32 v81, v86, v87
	v_cvt_pk_bf16_f32 v82, v104, v105
	v_cvt_pk_bf16_f32 v83, v102, v103
	global_store_dwordx4 v[98:99], v[80:83], off offset:256
	global_load_dwordx4 v[80:83], v[100:101], off
	s_nop 0
	global_load_dwordx4 v[84:87], v[100:101], off offset:16
	s_waitcnt vmcnt(1)
	v_mov_b32_e32 v88, v80
	s_waitcnt vmcnt(0)
	v_mov_b32_e32 v89, v84
	v_mov_b32_e32 v84, v81
	v_mov_b32_e32 v80, v82
	v_mov_b32_e32 v81, v86
	v_mov_b32_e32 v86, v83
	v_pk_add_f32 v[82:83], v[88:89], v[84:85]
	v_pk_add_f32 v[80:81], v[80:81], v[86:87]
	s_nop 0
	v_pk_add_f32 v[80:81], v[82:83], v[80:81]
	s_nop 0
	v_add_f32_e32 v80, v80, v81
	ds_bpermute_b32 v81, v167, v80
	s_waitcnt lgkmcnt(0)
	v_add_f32_e32 v82, v80, v81
	ds_bpermute_b32 v83, v168, v82
	v_add_u32_e32 v80, 0x90, v158
	v_ashrrev_i32_e32 v81, 31, v80
	v_lshlrev_b64 v[84:85], 7, v[80:81]
	v_lshl_add_u64 v[84:85], v[150:151], 0, v[84:85]
	s_waitcnt lgkmcnt(0)
	v_add_f32_e32 v82, v82, v83
	v_fmamk_f32 v82, v82, 0x3a000000, v215
	v_rsq_f32_e32 v86, v82
	s_nop 0
	v_lshlrev_b64 v[82:83], 14, v[96:97]
	v_lshl_add_u64 v[82:83], v[156:157], 0, v[82:83]
	v_pk_fma_f32 v[62:63], v[62:63], v[86:87], v[78:79] op_sel_hi:[1,0,1]
	v_pk_fma_f32 v[60:61], v[60:61], v[86:87], v[76:77] op_sel_hi:[1,0,1]
	v_pk_fma_f32 v[58:59], v[58:59], v[86:87], v[74:75] op_sel_hi:[1,0,1]
	v_pk_fma_f32 v[56:57], v[56:57], v[86:87], v[72:73] op_sel_hi:[1,0,1]
	v_pk_fma_f32 v[50:51], v[50:51], v[86:87], v[66:67] op_sel_hi:[1,0,1]
	v_pk_fma_f32 v[48:49], v[48:49], v[86:87], v[64:65] op_sel_hi:[1,0,1]
	v_pk_fma_f32 v[54:55], v[54:55], v[86:87], v[70:71] op_sel_hi:[1,0,1]
	v_pk_fma_f32 v[52:53], v[52:53], v[86:87], v[68:69] op_sel_hi:[1,0,1]
	v_max_f32_e32 v61, 0, v61
	v_max_f32_e32 v60, 0, v60
	v_max_f32_e32 v63, 0, v63
	v_max_f32_e32 v62, 0, v62
	v_max_f32_e32 v57, 0, v57
	v_max_f32_e32 v56, 0, v56
	v_max_f32_e32 v59, 0, v59
	v_max_f32_e32 v58, 0, v58
	v_max_f32_e32 v49, 0, v49
	v_max_f32_e32 v48, 0, v48
	v_max_f32_e32 v51, 0, v51
	v_max_f32_e32 v50, 0, v50
	v_max_f32_e32 v53, 0, v53
	v_max_f32_e32 v52, 0, v52
	v_max_f32_e32 v55, 0, v55
	v_max_f32_e32 v54, 0, v54
	v_pk_mul_f32 v[62:63], v[62:63], v[62:63]
	v_pk_mul_f32 v[60:61], v[60:61], v[60:61]
	v_pk_mul_f32 v[58:59], v[58:59], v[58:59]
	v_pk_mul_f32 v[56:57], v[56:57], v[56:57]
	v_pk_mul_f32 v[86:87], v[50:51], v[50:51]
	v_pk_mul_f32 v[88:89], v[48:49], v[48:49]
	v_cvt_pk_bf16_f32 v48, v60, v61
	v_cvt_pk_bf16_f32 v49, v62, v63
	v_cvt_pk_bf16_f32 v50, v56, v57
	v_cvt_pk_bf16_f32 v51, v58, v59
	v_pk_mul_f32 v[54:55], v[54:55], v[54:55]
	v_pk_mul_f32 v[52:53], v[52:53], v[52:53]
	global_store_dwordx4 v[82:83], v[48:51], off
	s_nop 1
	v_cvt_pk_bf16_f32 v48, v52, v53
	v_cvt_pk_bf16_f32 v49, v54, v55
	v_cvt_pk_bf16_f32 v50, v88, v89
	v_cvt_pk_bf16_f32 v51, v86, v87
	global_store_dwordx4 v[82:83], v[48:51], off offset:256
	global_load_dwordx4 v[48:51], v[84:85], off
	s_nop 0
	global_load_dwordx4 v[52:55], v[84:85], off offset:16
	s_waitcnt vmcnt(1)
	v_mov_b32_e32 v56, v48
	s_waitcnt vmcnt(0)
	v_mov_b32_e32 v57, v52
	v_mov_b32_e32 v52, v49
	v_mov_b32_e32 v48, v50
	v_mov_b32_e32 v49, v54
	v_mov_b32_e32 v54, v51
	v_pk_add_f32 v[50:51], v[56:57], v[52:53]
	v_pk_add_f32 v[48:49], v[48:49], v[54:55]
	s_nop 0
	v_pk_add_f32 v[48:49], v[50:51], v[48:49]
	s_nop 0
	v_add_f32_e32 v48, v48, v49
	ds_bpermute_b32 v49, v167, v48
	s_waitcnt lgkmcnt(0)
	v_add_f32_e32 v50, v48, v49
	ds_bpermute_b32 v51, v168, v50
	v_add_u32_e32 v48, 0xa0, v158
	v_ashrrev_i32_e32 v49, 31, v48
	v_lshlrev_b64 v[52:53], 7, v[48:49]
	v_lshl_add_u64 v[52:53], v[150:151], 0, v[52:53]
	s_waitcnt lgkmcnt(0)
;     __device__ __forceinline__ void operator()(const f32x4 (&acc)[2][2][4][2], const Unit& u, int wr, int wc, int fr, int fq) const {
;     ...
;             for (int m = 0; m < 4; ++m) { const int row = row0 + ai * HALF + m * 16; bf16_t* rowp = base + (size_t)row * ldc + col0;
;                 float inv = 1.f;
;                 if (ss) { const f32x4* sp = (const f32x4*)(ss + (size_t)row * 32 + fq * 8); const f32x4 p0 = sp[0], p1 = sp[1];
;                     float s = ((p0[0] + p0[1]) + (p0[2] + p0[3])) + ((p1[0] + p1[1]) + (p1[2] + p1[3]));
;                     s += __shfl_xor(s, 16); s += __shfl_xor(s, 32); inv = 1.0f / sqrtf(s * (1.f / 2048.f) + 1e-6f); }
;                 f32x4 va[2][2];
; #pragma unroll
;                 for (int bj = 0; bj < 2; ++bj) { f32x4 v0 = acc[ai][bj][m][0], v1 = acc[ai][bj][m][1];
;                     if (ss) { v0 = v0 * inv + swv[bj][0]; v1 = v1 * inv + swv[bj][1]; }
;                     if (ACT == 2) { v0 = __builtin_elementwise_max(v0, (f32x4){0.f, 0.f, 0.f, 0.f}); v1 = __builtin_elementwise_max(v1, (f32x4){0.f, 0.f, 0.f, 0.f}); v0 = v0 * v0; v1 = v1 * v1; }
;                     v0 = v0 * sc; v1 = v1 * sc;
;                     if (do_nrm) { float s2 = ((v0[0] * v0[0] + v0[1] * v0[1]) + (v0[2] * v0[2] + v0[3] * v0[3])) + ((v1[0] * v1[0] + v1[1] * v1[1]) + (v1[2] * v1[2] + v1[3] * v1[3]));
;                         s2 += __shfl_xor(s2, 16); s2 += __shfl_xor(s2, 32);
;                         if (fq == 0) nrm[((size_t)(((u.pn >> 3) * 4 + (row >> 12)) * 16 + (u.pn & 7) * 2 + bj) * 4096 + (row & 4095)) * 4 + wc] = s2; }
;                     va[bj][0] = v0; va[bj][1] = v1; }
;                 if (cu_out != nullptr && u.pn >= cu_from) {
;                     const f32x4 p0 = va[0][0] * va[1][0], p1 = va[0][1] * va[1][1];
;                     u32x4 w; w.x = cvt_pk_bf16(p0[0], p0[1]); w.y = cvt_pk_bf16(p0[2], p0[3]); w.z = cvt_pk_bf16(p1[0], p1[1]); w.w = cvt_pk_bf16(p1[2], p1[3]);
;                     *(u32x4*)(cu_out + (size_t)row * ldc + (u.pn - cu_from) * HALF + wc * 32 + 8 * fq) = w;
;                 } else {
; #pragma unroll
;                     for (int bj = 0; bj < 2; ++bj) { const f32x4 v0 = va[bj][0], v1 = va[bj][1];
;                         u32x4 w; w.x = cvt_pk_bf16(v0[0], v0[1]); w.y = cvt_pk_bf16(v0[2], v0[3]); w.z = cvt_pk_bf16(v1[0], v1[1]); w.w = cvt_pk_bf16(v1[2], v1[3]);
	v_add_f32_e32 v50, v50, v51
	v_fmamk_f32 v50, v50, 0x3a000000, v215
	v_rsq_f32_e32 v54, v50
	s_nop 0
	v_lshlrev_b64 v[50:51], 14, v[80:81]
	v_lshl_add_u64 v[50:51], v[156:157], 0, v[50:51]
	v_pk_fma_f32 v[46:47], v[46:47], v[54:55], v[78:79] op_sel_hi:[1,0,1]
	v_pk_fma_f32 v[44:45], v[44:45], v[54:55], v[76:77] op_sel_hi:[1,0,1]
	v_pk_fma_f32 v[42:43], v[42:43], v[54:55], v[74:75] op_sel_hi:[1,0,1]
	v_pk_fma_f32 v[40:41], v[40:41], v[54:55], v[72:73] op_sel_hi:[1,0,1]
	v_pk_fma_f32 v[34:35], v[34:35], v[54:55], v[66:67] op_sel_hi:[1,0,1]
	v_pk_fma_f32 v[32:33], v[32:33], v[54:55], v[64:65] op_sel_hi:[1,0,1]
	v_pk_fma_f32 v[38:39], v[38:39], v[54:55], v[70:71] op_sel_hi:[1,0,1]
	v_pk_fma_f32 v[36:37], v[36:37], v[54:55], v[68:69] op_sel_hi:[1,0,1]
	v_max_f32_e32 v45, 0, v45
	v_max_f32_e32 v44, 0, v44
	v_max_f32_e32 v47, 0, v47
	v_max_f32_e32 v46, 0, v46
	v_max_f32_e32 v41, 0, v41
	v_max_f32_e32 v40, 0, v40
	v_max_f32_e32 v43, 0, v43
	v_max_f32_e32 v42, 0, v42
	v_max_f32_e32 v33, 0, v33
	v_max_f32_e32 v32, 0, v32
	v_max_f32_e32 v35, 0, v35
	v_max_f32_e32 v34, 0, v34
	v_max_f32_e32 v37, 0, v37
	v_max_f32_e32 v36, 0, v36
	v_max_f32_e32 v39, 0, v39
	v_max_f32_e32 v38, 0, v38
	v_pk_mul_f32 v[46:47], v[46:47], v[46:47]
	v_pk_mul_f32 v[44:45], v[44:45], v[44:45]
	v_pk_mul_f32 v[42:43], v[42:43], v[42:43]
	v_pk_mul_f32 v[40:41], v[40:41], v[40:41]
	v_pk_mul_f32 v[54:55], v[34:35], v[34:35]
	v_pk_mul_f32 v[56:57], v[32:33], v[32:33]
	v_cvt_pk_bf16_f32 v32, v44, v45
	v_cvt_pk_bf16_f32 v33, v46, v47
	v_cvt_pk_bf16_f32 v34, v40, v41
	v_cvt_pk_bf16_f32 v35, v42, v43
	v_pk_mul_f32 v[38:39], v[38:39], v[38:39]
	v_pk_mul_f32 v[36:37], v[36:37], v[36:37]
	global_store_dwordx4 v[50:51], v[32:35], off
	s_nop 1
	v_cvt_pk_bf16_f32 v32, v36, v37
	v_cvt_pk_bf16_f32 v33, v38, v39
	v_cvt_pk_bf16_f32 v34, v56, v57
	v_cvt_pk_bf16_f32 v35, v54, v55
	global_store_dwordx4 v[50:51], v[32:35], off offset:256
	global_load_dwordx4 v[32:35], v[52:53], off
	s_nop 0
	global_load_dwordx4 v[36:39], v[52:53], off offset:16
	s_waitcnt vmcnt(1)
	v_mov_b32_e32 v40, v32
	s_waitcnt vmcnt(0)
	v_mov_b32_e32 v41, v36
	v_mov_b32_e32 v36, v33
	v_mov_b32_e32 v32, v34
	v_mov_b32_e32 v33, v38
	v_mov_b32_e32 v38, v35
	v_pk_add_f32 v[34:35], v[40:41], v[36:37]
	v_pk_add_f32 v[32:33], v[32:33], v[38:39]
	s_nop 0
	v_pk_add_f32 v[32:33], v[34:35], v[32:33]
	s_nop 0
	v_add_f32_e32 v32, v32, v33
	ds_bpermute_b32 v33, v167, v32
	s_waitcnt lgkmcnt(0)
	v_add_f32_e32 v34, v32, v33
	ds_bpermute_b32 v35, v168, v34
	v_add_u32_e32 v32, 0xb0, v158
	v_ashrrev_i32_e32 v33, 31, v32
	v_lshlrev_b64 v[36:37], 7, v[32:33]
	v_lshl_add_u64 v[36:37], v[150:151], 0, v[36:37]
	s_waitcnt lgkmcnt(0)
;     __device__ __forceinline__ void operator()(const f32x4 (&acc)[2][2][4][2], const Unit& u, int wr, int wc, int fr, int fq) const {
;     ...
;             for (int m = 0; m < 4; ++m) { const int row = row0 + ai * HALF + m * 16; bf16_t* rowp = base + (size_t)row * ldc + col0;
;                 float inv = 1.f;
;                 if (ss) { const f32x4* sp = (const f32x4*)(ss + (size_t)row * 32 + fq * 8); const f32x4 p0 = sp[0], p1 = sp[1];
;                     float s = ((p0[0] + p0[1]) + (p0[2] + p0[3])) + ((p1[0] + p1[1]) + (p1[2] + p1[3]));
;                     s += __shfl_xor(s, 16); s += __shfl_xor(s, 32); inv = 1.0f / sqrtf(s * (1.f / 2048.f) + 1e-6f); }
;                 f32x4 va[2][2];
; #pragma unroll
;                 for (int bj = 0; bj < 2; ++bj) { f32x4 v0 = acc[ai][bj][m][0], v1 = acc[ai][bj][m][1];
;                     if (ss) { v0 = v0 * inv + swv[bj][0]; v1 = v1 * inv + swv[bj][1]; }
;                     if (ACT == 2) { v0 = __builtin_elementwise_max(v0, (f32x4){0.f, 0.f, 0.f, 0.f}); v1 = __builtin_elementwise_max(v1, (f32x4){0.f, 0.f, 0.f, 0.f}); v0 = v0 * v0; v1 = v1 * v1; }
;                     v0 = v0 * sc; v1 = v1 * sc;
;                     if (do_nrm) { float s2 = ((v0[0] * v0[0] + v0[1] * v0[1]) + (v0[2] * v0[2] + v0[3] * v0[3])) + ((v1[0] * v1[0] + v1[1] * v1[1]) + (v1[2] * v1[2] + v1[3] * v1[3]));
;                         s2 += __shfl_xor(s2, 16); s2 += __shfl_xor(s2, 32);
;                         if (fq == 0) nrm[((size_t)(((u.pn >> 3) * 4 + (row >> 12)) * 16 + (u.pn & 7) * 2 + bj) * 4096 + (row & 4095)) * 4 + wc] = s2; }
;                     va[bj][0] = v0; va[bj][1] = v1; }
;                 if (cu_out != nullptr && u.pn >= cu_from) {
;                     const f32x4 p0 = va[0][0] * va[1][0], p1 = va[0][1] * va[1][1];
;                     u32x4 w; w.x = cvt_pk_bf16(p0[0], p0[1]); w.y = cvt_pk_bf16(p0[2], p0[3]); w.z = cvt_pk_bf16(p1[0], p1[1]); w.w = cvt_pk_bf16(p1[2], p1[3]);
;                     *(u32x4*)(cu_out + (size_t)row * ldc + (u.pn - cu_from) * HALF + wc * 32 + 8 * fq) = w;
;                 } else {
; #pragma unroll
;                     for (int bj = 0; bj < 2; ++bj) { const f32x4 v0 = va[bj][0], v1 = va[bj][1];
;                         u32x4 w; w.x = cvt_pk_bf16(v0[0], v0[1]); w.y = cvt_pk_bf16(v0[2], v0[3]); w.z = cvt_pk_bf16(v1[0], v1[1]); w.w = cvt_pk_bf16(v1[2], v1[3]);
	v_add_f32_e32 v34, v34, v35
	v_fmamk_f32 v34, v34, 0x3a000000, v215
	v_rsq_f32_e32 v38, v34
	s_nop 0
	v_lshlrev_b64 v[34:35], 14, v[48:49]
	v_lshl_add_u64 v[34:35], v[156:157], 0, v[34:35]
	v_pk_fma_f32 v[30:31], v[30:31], v[38:39], v[78:79] op_sel_hi:[1,0,1]
	v_pk_fma_f32 v[28:29], v[28:29], v[38:39], v[76:77] op_sel_hi:[1,0,1]
	v_pk_fma_f32 v[26:27], v[26:27], v[38:39], v[74:75] op_sel_hi:[1,0,1]
	v_pk_fma_f32 v[24:25], v[24:25], v[38:39], v[72:73] op_sel_hi:[1,0,1]
	v_pk_fma_f32 v[18:19], v[18:19], v[38:39], v[66:67] op_sel_hi:[1,0,1]
	v_pk_fma_f32 v[16:17], v[16:17], v[38:39], v[64:65] op_sel_hi:[1,0,1]
	v_pk_fma_f32 v[22:23], v[22:23], v[38:39], v[70:71] op_sel_hi:[1,0,1]
	v_pk_fma_f32 v[20:21], v[20:21], v[38:39], v[68:69] op_sel_hi:[1,0,1]
	v_max_f32_e32 v29, 0, v29
	v_max_f32_e32 v28, 0, v28
	v_max_f32_e32 v31, 0, v31
	v_max_f32_e32 v30, 0, v30
	v_max_f32_e32 v25, 0, v25
	v_max_f32_e32 v24, 0, v24
	v_max_f32_e32 v27, 0, v27
	v_max_f32_e32 v26, 0, v26
	v_max_f32_e32 v17, 0, v17
	v_max_f32_e32 v16, 0, v16
	v_max_f32_e32 v19, 0, v19
	v_max_f32_e32 v18, 0, v18
	v_max_f32_e32 v21, 0, v21
	v_max_f32_e32 v20, 0, v20
	v_max_f32_e32 v23, 0, v23
	v_max_f32_e32 v22, 0, v22
	v_pk_mul_f32 v[30:31], v[30:31], v[30:31]
	v_pk_mul_f32 v[28:29], v[28:29], v[28:29]
	v_pk_mul_f32 v[26:27], v[26:27], v[26:27]
	v_pk_mul_f32 v[24:25], v[24:25], v[24:25]
	v_pk_mul_f32 v[38:39], v[18:19], v[18:19]
	v_pk_mul_f32 v[40:41], v[16:17], v[16:17]
	v_cvt_pk_bf16_f32 v16, v28, v29
	v_cvt_pk_bf16_f32 v17, v30, v31
	v_cvt_pk_bf16_f32 v18, v24, v25
	v_cvt_pk_bf16_f32 v19, v26, v27
	v_pk_mul_f32 v[22:23], v[22:23], v[22:23]
	v_pk_mul_f32 v[20:21], v[20:21], v[20:21]
	global_store_dwordx4 v[34:35], v[16:19], off
	s_nop 1
	v_cvt_pk_bf16_f32 v16, v20, v21
	v_cvt_pk_bf16_f32 v17, v22, v23
	v_cvt_pk_bf16_f32 v18, v40, v41
	v_cvt_pk_bf16_f32 v19, v38, v39
	global_store_dwordx4 v[34:35], v[16:19], off offset:256
	global_load_dwordx4 v[16:19], v[36:37], off
	s_nop 0
	global_load_dwordx4 v[20:23], v[36:37], off offset:16
	s_waitcnt vmcnt(1)
	v_mov_b32_e32 v24, v16
	s_waitcnt vmcnt(0)
	v_mov_b32_e32 v25, v20
	v_mov_b32_e32 v20, v17
	v_mov_b32_e32 v16, v18
	v_mov_b32_e32 v17, v22
	v_mov_b32_e32 v22, v19
	v_pk_add_f32 v[18:19], v[24:25], v[20:21]
	v_pk_add_f32 v[16:17], v[16:17], v[22:23]
	s_nop 0
	v_pk_add_f32 v[16:17], v[18:19], v[16:17]
	s_nop 0
	v_add_f32_e32 v16, v16, v17
	ds_bpermute_b32 v17, v167, v16
	s_waitcnt lgkmcnt(0)
	v_add_f32_e32 v16, v16, v17
	ds_bpermute_b32 v17, v168, v16
	s_waitcnt lgkmcnt(0)
	v_add_f32_e32 v16, v16, v17
	v_fmamk_f32 v16, v16, 0x3a000000, v215
	v_rsq_f32_e32 v18, v16
	s_nop 0
	v_lshlrev_b64 v[16:17], 14, v[32:33]
	v_lshl_add_u64 v[16:17], v[156:157], 0, v[16:17]
	v_pk_fma_f32 v[14:15], v[14:15], v[18:19], v[78:79] op_sel_hi:[1,0,1]
	v_pk_fma_f32 v[12:13], v[12:13], v[18:19], v[76:77] op_sel_hi:[1,0,1]
	v_pk_fma_f32 v[10:11], v[10:11], v[18:19], v[74:75] op_sel_hi:[1,0,1]
	v_pk_fma_f32 v[8:9], v[8:9], v[18:19], v[72:73] op_sel_hi:[1,0,1]
	v_pk_fma_f32 v[2:3], v[2:3], v[18:19], v[66:67] op_sel_hi:[1,0,1]
	v_pk_fma_f32 v[0:1], v[0:1], v[18:19], v[64:65] op_sel_hi:[1,0,1]
	v_pk_fma_f32 v[6:7], v[6:7], v[18:19], v[70:71] op_sel_hi:[1,0,1]
	v_pk_fma_f32 v[4:5], v[4:5], v[18:19], v[68:69] op_sel_hi:[1,0,1]
	v_max_f32_e32 v13, 0, v13
	v_max_f32_e32 v12, 0, v12
	v_max_f32_e32 v15, 0, v15
	v_max_f32_e32 v14, 0, v14
	v_max_f32_e32 v9, 0, v9
	v_max_f32_e32 v8, 0, v8
	v_max_f32_e32 v11, 0, v11
	v_max_f32_e32 v10, 0, v10
	v_max_f32_e32 v1, 0, v1
	v_max_f32_e32 v0, 0, v0
	v_max_f32_e32 v3, 0, v3
	v_max_f32_e32 v2, 0, v2
	s_andn2_b64 vcc, exec, s[40:41]
	v_max_f32_e32 v5, 0, v5
	v_max_f32_e32 v4, 0, v4
	v_max_f32_e32 v7, 0, v7
	v_max_f32_e32 v6, 0, v6
	v_pk_mul_f32 v[14:15], v[14:15], v[14:15]
	v_pk_mul_f32 v[12:13], v[12:13], v[12:13]
	v_pk_mul_f32 v[10:11], v[10:11], v[10:11]
	v_pk_mul_f32 v[8:9], v[8:9], v[8:9]
	v_pk_mul_f32 v[18:19], v[2:3], v[2:3]
	v_pk_mul_f32 v[20:21], v[0:1], v[0:1]
	v_cvt_pk_bf16_f32 v0, v12, v13
	v_cvt_pk_bf16_f32 v1, v14, v15
	v_cvt_pk_bf16_f32 v2, v8, v9
	v_cvt_pk_bf16_f32 v3, v10, v11
	s_mov_b64 s[40:41], -1
	v_pk_mul_f32 v[6:7], v[6:7], v[6:7]
	v_pk_mul_f32 v[4:5], v[4:5], v[4:5]
	global_store_dwordx4 v[16:17], v[0:3], off
	s_nop 1
	v_cvt_pk_bf16_f32 v0, v4, v5
	v_cvt_pk_bf16_f32 v1, v6, v7
	v_cvt_pk_bf16_f32 v2, v20, v21
	v_cvt_pk_bf16_f32 v3, v18, v19
	global_store_dwordx4 v[16:17], v[0:3], off offset:256
	s_cbranch_vccnz .LBB0_47
	s_andn2_b64 vcc, exec, s[14:15]
	s_cbranch_vccnz .LBB0_46
	s_barrier
	s_branch .LBB0_46

;     __device__ __forceinline__ void operator()(const f32x4 (&acc)[2][2][4][2], const Unit& u, int wr, int wc, int fr, int fq) const {
;     ...
;             for (int m = 0; m < 4; ++m) { const int row = row0 + ai * HALF + m * 16; bf16_t* rowp = base + (size_t)row * ldc + col0;
;                 float inv = 1.f;
;                 if (ss) { const f32x4* sp = (const f32x4*)(ss + (size_t)row * 32 + fq * 8); const f32x4 p0 = sp[0], p1 = sp[1];
;                     float s = ((p0[0] + p0[1]) + (p0[2] + p0[3])) + ((p1[0] + p1[1]) + (p1[2] + p1[3]));
;                     s += __shfl_xor(s, 16); s += __shfl_xor(s, 32); inv = 1.0f / sqrtf(s * (1.f / 2048.f) + 1e-6f); }
.LBB0_407:
	v_lshl_add_u32 v162, s7, 8, v153
	v_ashrrev_i32_e32 v163, 31, v162
	s_and_b64 vcc, exec, s[46:47]
	v_mov_b32_e32 v166, 1.0
	s_cbranch_vccnz .LBB0_409
	v_lshlrev_b64 v[160:161], 7, v[162:163]
	v_lshl_add_u64 v[160:161], v[154:155], 0, v[160:161]
	global_load_dwordx4 v[164:167], v[160:161], off
	global_load_dwordx4 v[168:171], v[160:161], off offset:16
	v_cmp_lt_i32_e32 vcc, v232, v220
	s_waitcnt vmcnt(0)
	v_mov_b32_e32 v160, v164
	v_mov_b32_e32 v161, v168
	v_mov_b32_e32 v168, v165
	v_mov_b32_e32 v164, v166
	v_mov_b32_e32 v165, v170
	v_mov_b32_e32 v170, v167
	v_pk_add_f32 v[160:161], v[160:161], v[168:169]
	v_pk_add_f32 v[164:165], v[164:165], v[170:171]
	s_nop 0
	v_pk_add_f32 v[160:161], v[160:161], v[164:165]
	s_nop 0
	v_add_f32_e32 v160, v160, v161
	v_cndmask_b32_e32 v161, v217, v232, vcc
	v_lshlrev_b32_e32 v161, 2, v161
	ds_bpermute_b32 v161, v161, v160
	v_cmp_lt_i32_e32 vcc, v226, v220
	s_waitcnt lgkmcnt(0)
	v_add_f32_e32 v160, v160, v161
	v_cndmask_b32_e32 v161, v217, v226, vcc
	v_lshlrev_b32_e32 v161, 2, v161
	ds_bpermute_b32 v161, v161, v160
	s_waitcnt lgkmcnt(0)
	v_add_f32_e32 v160, v160, v161
	v_fmamk_f32 v160, v160, 0x3a000000, v215
	v_rsq_f32_e32 v166, v160
	s_nop 0

;     __device__ __forceinline__ void operator()(const f32x4 (&acc)[2][2][4][2], const Unit& u, int wr, int wc, int fr, int fq) const {
;     ...
;             for (int m = 0; m < 4; ++m) { const int row = row0 + ai * HALF + m * 16; bf16_t* rowp = base + (size_t)row * ldc + col0;
;                 float inv = 1.f;
;                 if (ss) { const f32x4* sp = (const f32x4*)(ss + (size_t)row * 32 + fq * 8); const f32x4 p0 = sp[0], p1 = sp[1];
;                     float s = ((p0[0] + p0[1]) + (p0[2] + p0[3])) + ((p1[0] + p1[1]) + (p1[2] + p1[3]));
;                     s += __shfl_xor(s, 16); s += __shfl_xor(s, 32); inv = 1.0f / sqrtf(s * (1.f / 2048.f) + 1e-6f); }
.LBB0_425:
	v_or_b32_e32 v132, 16, v162
	v_ashrrev_i32_e32 v133, 31, v132
	s_and_b64 vcc, exec, s[46:47]
	v_mov_b32_e32 v138, 1.0
	s_cbranch_vccnz .LBB0_427
	v_lshlrev_b64 v[134:135], 7, v[132:133]
	v_lshl_add_u64 v[134:135], v[154:155], 0, v[134:135]
	global_load_dwordx4 v[138:141], v[134:135], off
	global_load_dwordx4 v[164:167], v[134:135], off offset:16
	v_cmp_lt_i32_e32 vcc, v232, v220
	s_waitcnt vmcnt(1)
	v_mov_b32_e32 v134, v138
	s_waitcnt vmcnt(0)
	v_mov_b32_e32 v135, v164
	v_mov_b32_e32 v164, v139
	v_mov_b32_e32 v138, v140
	v_mov_b32_e32 v139, v166
	v_mov_b32_e32 v166, v141
	v_pk_add_f32 v[134:135], v[134:135], v[164:165]
	v_pk_add_f32 v[138:139], v[138:139], v[166:167]
	s_nop 0
	v_pk_add_f32 v[134:135], v[134:135], v[138:139]
	s_waitcnt lgkmcnt(0)
	v_add_f32_e32 v129, v134, v135
	v_cndmask_b32_e32 v134, v217, v232, vcc
	v_lshlrev_b32_e32 v134, 2, v134
	ds_bpermute_b32 v134, v134, v129
	v_cmp_lt_i32_e32 vcc, v226, v220
	s_waitcnt lgkmcnt(0)
	v_add_f32_e32 v129, v129, v134
	v_cndmask_b32_e32 v134, v217, v226, vcc
	v_lshlrev_b32_e32 v134, 2, v134
	ds_bpermute_b32 v134, v134, v129
	s_waitcnt lgkmcnt(0)
	v_add_f32_e32 v129, v129, v134
	v_fmamk_f32 v129, v129, 0x3a000000, v215
	v_rsq_f32_e32 v138, v129
	s_nop 0

;     __device__ __forceinline__ void operator()(const f32x4 (&acc)[2][2][4][2], const Unit& u, int wr, int wc, int fr, int fq) const {
;     ...
;             for (int m = 0; m < 4; ++m) { const int row = row0 + ai * HALF + m * 16; bf16_t* rowp = base + (size_t)row * ldc + col0;
;                 float inv = 1.f;
;                 if (ss) { const f32x4* sp = (const f32x4*)(ss + (size_t)row * 32 + fq * 8); const f32x4 p0 = sp[0], p1 = sp[1];
;                     float s = ((p0[0] + p0[1]) + (p0[2] + p0[3])) + ((p1[0] + p1[1]) + (p1[2] + p1[3]));
;                     s += __shfl_xor(s, 16); s += __shfl_xor(s, 32); inv = 1.0f / sqrtf(s * (1.f / 2048.f) + 1e-6f); }
.LBB0_443:
	v_or_b32_e32 v112, 32, v162
	v_ashrrev_i32_e32 v113, 31, v112
	s_and_b64 vcc, exec, s[46:47]
	v_mov_b32_e32 v116, 1.0
	s_cbranch_vccnz .LBB0_445
	v_lshlrev_b64 v[114:115], 7, v[112:113]
	v_lshl_add_u64 v[118:119], v[154:155], 0, v[114:115]
	global_load_dwordx4 v[114:117], v[118:119], off
	s_nop 0
	global_load_dwordx4 v[118:121], v[118:119], off offset:16
	v_cmp_lt_i32_e32 vcc, v232, v220
	s_waitcnt vmcnt(1)
	v_mov_b32_e32 v122, v114
	s_waitcnt vmcnt(0)
	v_mov_b32_e32 v123, v118
	v_mov_b32_e32 v118, v115
	v_pk_add_f32 v[114:115], v[122:123], v[118:119]
	v_mov_b32_e32 v118, v116
	v_mov_b32_e32 v119, v120
	v_mov_b32_e32 v120, v117
	v_pk_add_f32 v[116:117], v[118:119], v[120:121]
	s_nop 0
	v_pk_add_f32 v[114:115], v[114:115], v[116:117]
	s_nop 0
	v_add_f32_e32 v114, v114, v115
	v_cndmask_b32_e32 v115, v217, v232, vcc
	v_lshlrev_b32_e32 v115, 2, v115
	ds_bpermute_b32 v115, v115, v114
	v_cmp_lt_i32_e32 vcc, v226, v220
	s_waitcnt lgkmcnt(0)
	v_add_f32_e32 v114, v114, v115
	v_cndmask_b32_e32 v115, v217, v226, vcc
	v_lshlrev_b32_e32 v115, 2, v115
	ds_bpermute_b32 v115, v115, v114
	s_waitcnt lgkmcnt(0)
	v_add_f32_e32 v114, v114, v115
	v_fmamk_f32 v114, v114, 0x3a000000, v215
	v_rsq_f32_e32 v116, v114
	s_nop 0

;     __device__ __forceinline__ void operator()(const f32x4 (&acc)[2][2][4][2], const Unit& u, int wr, int wc, int fr, int fq) const {
;     ...
;             for (int m = 0; m < 4; ++m) { const int row = row0 + ai * HALF + m * 16; bf16_t* rowp = base + (size_t)row * ldc + col0;
;                 float inv = 1.f;
;                 if (ss) { const f32x4* sp = (const f32x4*)(ss + (size_t)row * 32 + fq * 8); const f32x4 p0 = sp[0], p1 = sp[1];
;                     float s = ((p0[0] + p0[1]) + (p0[2] + p0[3])) + ((p1[0] + p1[1]) + (p1[2] + p1[3]));
;                     s += __shfl_xor(s, 16); s += __shfl_xor(s, 32); inv = 1.0f / sqrtf(s * (1.f / 2048.f) + 1e-6f); }
.LBB0_456:
	v_or_b32_e32 v96, 48, v162
	v_ashrrev_i32_e32 v97, 31, v96
	s_and_b64 vcc, exec, s[46:47]
	v_mov_b32_e32 v100, 1.0
	s_cbranch_vccnz .LBB0_458
	v_lshlrev_b64 v[98:99], 7, v[96:97]
	v_lshl_add_u64 v[102:103], v[154:155], 0, v[98:99]
	global_load_dwordx4 v[98:101], v[102:103], off
	s_nop 0
	global_load_dwordx4 v[102:105], v[102:103], off offset:16
	v_cmp_lt_i32_e32 vcc, v232, v220
	s_waitcnt vmcnt(1)
	v_mov_b32_e32 v106, v98
	s_waitcnt vmcnt(0)
	v_mov_b32_e32 v107, v102
	v_mov_b32_e32 v102, v99
	v_pk_add_f32 v[98:99], v[106:107], v[102:103]
	v_mov_b32_e32 v102, v100
	v_mov_b32_e32 v103, v104
	v_mov_b32_e32 v104, v101
	v_pk_add_f32 v[100:101], v[102:103], v[104:105]
	s_nop 0
	v_pk_add_f32 v[98:99], v[98:99], v[100:101]
	s_nop 0
	v_add_f32_e32 v98, v98, v99
	v_cndmask_b32_e32 v99, v217, v232, vcc
	v_lshlrev_b32_e32 v99, 2, v99
	ds_bpermute_b32 v99, v99, v98
	v_cmp_lt_i32_e32 vcc, v226, v220
	s_waitcnt lgkmcnt(0)
	v_add_f32_e32 v98, v98, v99
	v_cndmask_b32_e32 v99, v217, v226, vcc
	v_lshlrev_b32_e32 v99, 2, v99
	ds_bpermute_b32 v99, v99, v98
	s_waitcnt lgkmcnt(0)
	v_add_f32_e32 v98, v98, v99
	v_fmamk_f32 v98, v98, 0x3a000000, v215
	v_rsq_f32_e32 v100, v98
	s_nop 0

;     __device__ __forceinline__ void operator()(const f32x4 (&acc)[2][2][4][2], const Unit& u, int wr, int wc, int fr, int fq) const {
;     ...
;             for (int m = 0; m < 4; ++m) { const int row = row0 + ai * HALF + m * 16; bf16_t* rowp = base + (size_t)row * ldc + col0;
;                 float inv = 1.f;
;                 if (ss) { const f32x4* sp = (const f32x4*)(ss + (size_t)row * 32 + fq * 8); const f32x4 p0 = sp[0], p1 = sp[1];
;                     float s = ((p0[0] + p0[1]) + (p0[2] + p0[3])) + ((p1[0] + p1[1]) + (p1[2] + p1[3]));
;                     s += __shfl_xor(s, 16); s += __shfl_xor(s, 32); inv = 1.0f / sqrtf(s * (1.f / 2048.f) + 1e-6f); }
.LBB0_469:
	v_add_u32_e32 v80, 0x80, v162
	v_ashrrev_i32_e32 v81, 31, v80
	s_and_b64 vcc, exec, s[46:47]
	v_mov_b32_e32 v86, 1.0
	s_cbranch_vccnz .LBB0_471
	v_lshlrev_b64 v[82:83], 7, v[80:81]
	v_lshl_add_u64 v[86:87], v[154:155], 0, v[82:83]
	global_load_dwordx4 v[82:85], v[86:87], off
	s_nop 0
	global_load_dwordx4 v[86:89], v[86:87], off offset:16
	v_cmp_lt_i32_e32 vcc, v232, v220
	s_waitcnt vmcnt(1)
	v_mov_b32_e32 v90, v82
	s_waitcnt vmcnt(0)
	v_mov_b32_e32 v91, v86
	v_mov_b32_e32 v86, v83
	v_pk_add_f32 v[82:83], v[90:91], v[86:87]
	v_mov_b32_e32 v86, v84
	v_mov_b32_e32 v87, v88
	v_mov_b32_e32 v88, v85
	v_pk_add_f32 v[84:85], v[86:87], v[88:89]
	s_nop 0
	v_pk_add_f32 v[82:83], v[82:83], v[84:85]
	s_nop 0
	v_add_f32_e32 v82, v82, v83
	v_cndmask_b32_e32 v83, v217, v232, vcc
	v_lshlrev_b32_e32 v83, 2, v83
	ds_bpermute_b32 v83, v83, v82
	v_cmp_lt_i32_e32 vcc, v226, v220
	s_waitcnt lgkmcnt(0)
	v_add_f32_e32 v82, v82, v83
	v_cndmask_b32_e32 v83, v217, v226, vcc
	v_lshlrev_b32_e32 v83, 2, v83
	ds_bpermute_b32 v83, v83, v82
	s_waitcnt lgkmcnt(0)
	v_add_f32_e32 v82, v82, v83
	v_fmamk_f32 v82, v82, 0x3a000000, v215
	v_rsq_f32_e32 v86, v82
	s_nop 0

;     __device__ __forceinline__ void operator()(const f32x4 (&acc)[2][2][4][2], const Unit& u, int wr, int wc, int fr, int fq) const {
;     ...
;             for (int m = 0; m < 4; ++m) { const int row = row0 + ai * HALF + m * 16; bf16_t* rowp = base + (size_t)row * ldc + col0;
;                 float inv = 1.f;
;                 if (ss) { const f32x4* sp = (const f32x4*)(ss + (size_t)row * 32 + fq * 8); const f32x4 p0 = sp[0], p1 = sp[1];
;                     float s = ((p0[0] + p0[1]) + (p0[2] + p0[3])) + ((p1[0] + p1[1]) + (p1[2] + p1[3]));
;                     s += __shfl_xor(s, 16); s += __shfl_xor(s, 32); inv = 1.0f / sqrtf(s * (1.f / 2048.f) + 1e-6f); }
.LBB0_482:
	v_add_u32_e32 v64, 0x90, v162
	v_ashrrev_i32_e32 v65, 31, v64
	s_and_b64 vcc, exec, s[46:47]
	v_mov_b32_e32 v68, 1.0
	s_cbranch_vccnz .LBB0_484
	v_lshlrev_b64 v[66:67], 7, v[64:65]
	v_lshl_add_u64 v[70:71], v[154:155], 0, v[66:67]
	global_load_dwordx4 v[66:69], v[70:71], off
	global_load_dwordx4 v[74:77], v[70:71], off offset:16
	v_cmp_lt_i32_e32 vcc, v232, v220
	s_waitcnt vmcnt(1)
	v_mov_b32_e32 v70, v66
	s_waitcnt vmcnt(0)
	v_mov_b32_e32 v71, v74
	v_mov_b32_e32 v74, v67
	v_pk_add_f32 v[66:67], v[70:71], v[74:75]
	v_mov_b32_e32 v70, v68
	v_mov_b32_e32 v71, v76
	v_mov_b32_e32 v76, v69
	v_pk_add_f32 v[68:69], v[70:71], v[76:77]
	s_nop 0
	v_pk_add_f32 v[66:67], v[66:67], v[68:69]
	s_nop 0
	v_add_f32_e32 v66, v66, v67
	v_cndmask_b32_e32 v67, v217, v232, vcc
	v_lshlrev_b32_e32 v67, 2, v67
	ds_bpermute_b32 v67, v67, v66
	v_cmp_lt_i32_e32 vcc, v226, v220
	s_waitcnt lgkmcnt(0)
	v_add_f32_e32 v66, v66, v67
	v_cndmask_b32_e32 v67, v217, v226, vcc
	v_lshlrev_b32_e32 v67, 2, v67
	ds_bpermute_b32 v67, v67, v66
	s_waitcnt lgkmcnt(0)
	v_add_f32_e32 v66, v66, v67
	v_fmamk_f32 v66, v66, 0x3a000000, v215
	v_rsq_f32_e32 v68, v66
	s_nop 0

;     __device__ __forceinline__ void operator()(const f32x4 (&acc)[2][2][4][2], const Unit& u, int wr, int wc, int fr, int fq) const {
;     ...
;             for (int m = 0; m < 4; ++m) { const int row = row0 + ai * HALF + m * 16; bf16_t* rowp = base + (size_t)row * ldc + col0;
;                 float inv = 1.f;
;                 if (ss) { const f32x4* sp = (const f32x4*)(ss + (size_t)row * 32 + fq * 8); const f32x4 p0 = sp[0], p1 = sp[1];
;                     float s = ((p0[0] + p0[1]) + (p0[2] + p0[3])) + ((p1[0] + p1[1]) + (p1[2] + p1[3]));
;                     s += __shfl_xor(s, 16); s += __shfl_xor(s, 32); inv = 1.0f / sqrtf(s * (1.f / 2048.f) + 1e-6f); }
.LBB0_495:
	v_add_u32_e32 v48, 0xa0, v162
	v_ashrrev_i32_e32 v49, 31, v48
	s_and_b64 vcc, exec, s[46:47]
	v_mov_b32_e32 v52, 1.0
	s_cbranch_vccnz .LBB0_497
	v_lshlrev_b64 v[50:51], 7, v[48:49]
	v_lshl_add_u64 v[54:55], v[154:155], 0, v[50:51]
	global_load_dwordx4 v[50:53], v[54:55], off
	s_nop 0
	global_load_dwordx4 v[54:57], v[54:55], off offset:16
	v_cmp_lt_i32_e32 vcc, v232, v220
	s_waitcnt vmcnt(1)
	v_mov_b32_e32 v58, v50
	s_waitcnt vmcnt(0)
	v_mov_b32_e32 v59, v54
	v_mov_b32_e32 v54, v51
	v_pk_add_f32 v[50:51], v[58:59], v[54:55]
	v_mov_b32_e32 v54, v52
	v_mov_b32_e32 v55, v56
	v_mov_b32_e32 v56, v53
	v_pk_add_f32 v[52:53], v[54:55], v[56:57]
	s_nop 0
	v_pk_add_f32 v[50:51], v[50:51], v[52:53]
	s_nop 0
	v_add_f32_e32 v50, v50, v51
	v_cndmask_b32_e32 v51, v217, v232, vcc
	v_lshlrev_b32_e32 v51, 2, v51
	ds_bpermute_b32 v51, v51, v50
	v_cmp_lt_i32_e32 vcc, v226, v220
	s_waitcnt lgkmcnt(0)
	v_add_f32_e32 v50, v50, v51
	v_cndmask_b32_e32 v51, v217, v226, vcc
	v_lshlrev_b32_e32 v51, 2, v51
	ds_bpermute_b32 v51, v51, v50
	s_waitcnt lgkmcnt(0)
	v_add_f32_e32 v50, v50, v51
	v_fmamk_f32 v50, v50, 0x3a000000, v215
	v_rsq_f32_e32 v52, v50
	s_nop 0

;     __device__ __forceinline__ void operator()(const f32x4 (&acc)[2][2][4][2], const Unit& u, int wr, int wc, int fr, int fq) const {
;     ...
;             for (int m = 0; m < 4; ++m) { const int row = row0 + ai * HALF + m * 16; bf16_t* rowp = base + (size_t)row * ldc + col0;
;                 float inv = 1.f;
;                 if (ss) { const f32x4* sp = (const f32x4*)(ss + (size_t)row * 32 + fq * 8); const f32x4 p0 = sp[0], p1 = sp[1];
;                     float s = ((p0[0] + p0[1]) + (p0[2] + p0[3])) + ((p1[0] + p1[1]) + (p1[2] + p1[3]));
;                     s += __shfl_xor(s, 16); s += __shfl_xor(s, 32); inv = 1.0f / sqrtf(s * (1.f / 2048.f) + 1e-6f); }
.LBB0_508:
	v_add_u32_e32 v16, 0xb0, v162
	v_ashrrev_i32_e32 v17, 31, v16
	s_and_b64 vcc, exec, s[46:47]
	v_mov_b32_e32 v20, 1.0
	s_cbranch_vccnz .LBB0_510
	v_lshlrev_b64 v[18:19], 7, v[16:17]
	v_lshl_add_u64 v[22:23], v[154:155], 0, v[18:19]
	global_load_dwordx4 v[18:21], v[22:23], off
	s_nop 0
	global_load_dwordx4 v[22:25], v[22:23], off offset:16
	v_cmp_lt_i32_e32 vcc, v232, v220
	s_waitcnt vmcnt(1)
	v_mov_b32_e32 v26, v18
	s_waitcnt vmcnt(0)
	v_mov_b32_e32 v27, v22
	v_mov_b32_e32 v22, v19
	v_pk_add_f32 v[18:19], v[26:27], v[22:23]
	v_mov_b32_e32 v22, v20
	v_mov_b32_e32 v23, v24
	v_mov_b32_e32 v24, v21
	v_pk_add_f32 v[20:21], v[22:23], v[24:25]
	s_nop 0
	v_pk_add_f32 v[18:19], v[18:19], v[20:21]
	s_nop 0
	v_add_f32_e32 v18, v18, v19
	v_cndmask_b32_e32 v19, v217, v232, vcc
	v_lshlrev_b32_e32 v19, 2, v19
	ds_bpermute_b32 v19, v19, v18
	v_cmp_lt_i32_e32 vcc, v226, v220
	s_waitcnt lgkmcnt(0)
	v_add_f32_e32 v18, v18, v19
	v_cndmask_b32_e32 v19, v217, v226, vcc
	v_lshlrev_b32_e32 v19, 2, v19
	ds_bpermute_b32 v19, v19, v18
	s_waitcnt lgkmcnt(0)
	v_add_f32_e32 v18, v18, v19
	v_fmamk_f32 v18, v18, 0x3a000000, v215
	v_rsq_f32_e32 v20, v18
	s_nop 0
